# v27 + hgA score tile loop and hgC causal score tile loop unrolled wave-uniform with all LDS fragment reads in flight (saddr stores, no per-lane loop)
# speedup vs baseline: 1.0020x; 1.0020x over previous
; __device__ __forceinline__ bf16_t f2bf(float f) { unsigned u = __float_as_uint(f); u += 0x7FFFu + ((u >> 16) & 1u); return (bf16_t)(u >> 16); }
; template <bool SA, bool SB> __device__ __forceinline__ f32x4 mma_tile64(const bf16_t* A, int ra0, const bf16_t* Bt, int rb0, int lane) {
;     ...
;     for (int kk = 0; kk < 2; ++kk) {
;         const bf16x8 a = *(const bf16x8*)(A + ra * 72 + (((kk * 4 + q) ^ sa) << 3));
;         const bf16x8 b = *(const bf16x8*)(Bt + rb * 72 + (((kk * 4 + q) ^ sb) << 3));
;         acc = __builtin_amdgcn_mfma_f32_16x16x32_bf16(a, b, acc, 0, 0, 0);
; __device__ __forceinline__ void hgA_item(const Bufs& B, int l, int it, unsigned char* shm, const float* hlb, const HgRegs& R) {
;     ...
;     for (int tile = wid; tile < 64; tile += 8) {
;         const int tm = tile >> 3, tn = tile & 7;
;         const f32x4 acc = mma_tile64<true, true>(iT, tm * 16, kdT, tn * 16, lane);
; #pragma unroll
;         for (int j = 0; j < 4; ++j) Sg[(tm * 16 + (lane >> 4) * 4 + j) * 128 + tn * 16 + (lane & 15)] = f2bf(acc[j]);
;     }
.LBB0_541:
	s_or_b64 exec, exec, s[2:3]
	v_ashrrev_i32_e32 v22, 6, v42
	v_cmp_gt_i32_e32 vcc, 64, v22
	s_waitcnt lgkmcnt(0)
	s_barrier
	s_mov_b64 s[2:3], exec
	s_ashr_i32 s23, s22, 31
	s_lshl_b64 s[22:23], s[22:23], 15
	s_add_u32 s22, s27, s22
	s_addc_u32 s23, s29, s23
	v_lshrrev_b32_e32 v17, 1, v42
	v_and_b32_e32 v16, 15, v42
	v_and_b32_e32 v17, 24, v17
	v_lshrrev_b32_e32 v19, 2, v42
	v_or_b32_e32 v18, 32, v17
	v_and_b32_e32 v19, 12, v19
	v_lshl_or_b32 v36, v22, 4, v16
	v_mul_u32_u24_e32 v34, s76, v36
	v_bitop3_b32 v24, v36, v17, 56 bitop3:0x6c
	v_bitop3_b32 v25, v36, v18, 56 bitop3:0x6c
	v_lshl_add_u32 v24, v24, 1, v34
	v_lshl_add_u32 v25, v25, 1, v34
	ds_read_b128 v[28:31], v24 offset:32768
	ds_read_b128 v[32:35], v25 offset:32768
	v_mul_u32_u24_e32 v38, s76, v16
	v_add_u32_e32 v38, 0x4000, v38
	v_mov_b32_e32 v39, v16
	v_bitop3_b32 v24, v39, v17, 56 bitop3:0x6c
	v_bitop3_b32 v25, v39, v18, 56 bitop3:0x6c
	v_lshl_add_u32 v24, v24, 1, v38
	v_lshl_add_u32 v25, v25, 1, v38
	ds_read_b128 v[64:67], v24 offset:34816
	ds_read_b128 v[68:71], v25 offset:34816
	v_or_b32_e32 v39, 16, v16
	v_bitop3_b32 v24, v39, v17, 56 bitop3:0x6c
	v_bitop3_b32 v25, v39, v18, 56 bitop3:0x6c
	v_lshl_add_u32 v24, v24, 1, v38
	v_lshl_add_u32 v25, v25, 1, v38
	ds_read_b128 v[72:75], v24 offset:37120
	ds_read_b128 v[76:79], v25 offset:37120
	v_or_b32_e32 v39, 32, v16
	v_bitop3_b32 v24, v39, v17, 56 bitop3:0x6c
	v_bitop3_b32 v25, v39, v18, 56 bitop3:0x6c
	v_lshl_add_u32 v24, v24, 1, v38
	v_lshl_add_u32 v25, v25, 1, v38
	ds_read_b128 v[80:83], v24 offset:39424
	ds_read_b128 v[84:87], v25 offset:39424
	v_or_b32_e32 v39, 48, v16
	v_bitop3_b32 v24, v39, v17, 56 bitop3:0x6c
	v_bitop3_b32 v25, v39, v18, 56 bitop3:0x6c
	v_lshl_add_u32 v24, v24, 1, v38
	v_lshl_add_u32 v25, v25, 1, v38
	ds_read_b128 v[88:91], v24 offset:41728
	ds_read_b128 v[92:95], v25 offset:41728
	v_or_b32_e32 v39, 64, v16
	v_bitop3_b32 v24, v39, v17, 56 bitop3:0x6c
	v_bitop3_b32 v25, v39, v18, 56 bitop3:0x6c
	v_lshl_add_u32 v24, v24, 1, v38
	v_lshl_add_u32 v25, v25, 1, v38
	ds_read_b128 v[96:99], v24 offset:44032
	ds_read_b128 v[100:103], v25 offset:44032
	v_or_b32_e32 v39, 80, v16
	v_bitop3_b32 v24, v39, v17, 56 bitop3:0x6c
	v_bitop3_b32 v25, v39, v18, 56 bitop3:0x6c
	v_lshl_add_u32 v24, v24, 1, v38
	v_lshl_add_u32 v25, v25, 1, v38
	ds_read_b128 v[104:107], v24 offset:46336
	ds_read_b128 v[108:111], v25 offset:46336
	v_or_b32_e32 v39, 96, v16
	v_bitop3_b32 v24, v39, v17, 56 bitop3:0x6c
	v_bitop3_b32 v25, v39, v18, 56 bitop3:0x6c
	v_lshl_add_u32 v24, v24, 1, v38
	v_lshl_add_u32 v25, v25, 1, v38
	ds_read_b128 v[112:115], v24 offset:48640
	ds_read_b128 v[116:119], v25 offset:48640
	v_or_b32_e32 v39, 112, v16
	v_bitop3_b32 v24, v39, v17, 56 bitop3:0x6c
	v_bitop3_b32 v25, v39, v18, 56 bitop3:0x6c
	v_lshl_add_u32 v24, v24, 1, v38
	v_lshl_add_u32 v25, v25, 1, v38
	ds_read_b128 v[120:123], v24 offset:50944
	ds_read_b128 v[124:127], v25 offset:50944
	v_lshlrev_b32_e32 v20, 8, v19
	v_lshl_add_u32 v20, v36, 1, v20
	s_waitcnt lgkmcnt(14)
	v_mfma_f32_16x16x32_bf16 v[64:67], v[64:67], v[28:31], 0
	v_mfma_f32_16x16x32_bf16 v[64:67], v[68:71], v[32:35], v[64:67]
	s_waitcnt lgkmcnt(12)
	v_mfma_f32_16x16x32_bf16 v[72:75], v[72:75], v[28:31], 0
	v_mfma_f32_16x16x32_bf16 v[72:75], v[76:79], v[32:35], v[72:75]
	s_waitcnt lgkmcnt(10)
	v_mfma_f32_16x16x32_bf16 v[80:83], v[80:83], v[28:31], 0
	v_mfma_f32_16x16x32_bf16 v[80:83], v[84:87], v[32:35], v[80:83]
	s_waitcnt lgkmcnt(8)
	v_mfma_f32_16x16x32_bf16 v[88:91], v[88:91], v[28:31], 0
	v_mfma_f32_16x16x32_bf16 v[88:91], v[92:95], v[32:35], v[88:91]
	s_waitcnt lgkmcnt(6)
	v_mfma_f32_16x16x32_bf16 v[96:99], v[96:99], v[28:31], 0
	v_mfma_f32_16x16x32_bf16 v[96:99], v[100:103], v[32:35], v[96:99]
	s_waitcnt lgkmcnt(4)
	v_mfma_f32_16x16x32_bf16 v[104:107], v[104:107], v[28:31], 0
	v_mfma_f32_16x16x32_bf16 v[104:107], v[108:111], v[32:35], v[104:107]
	s_waitcnt lgkmcnt(2)
	v_mfma_f32_16x16x32_bf16 v[112:115], v[112:115], v[28:31], 0
	v_mfma_f32_16x16x32_bf16 v[112:115], v[116:119], v[32:35], v[112:115]
	s_waitcnt lgkmcnt(0)
; __device__ __forceinline__ bf16_t f2bf(float f) { unsigned u = __float_as_uint(f); u += 0x7FFFu + ((u >> 16) & 1u); return (bf16_t)(u >> 16); }
; __device__ __forceinline__ void hgA_item(const Bufs& B, int l, int it, unsigned char* shm, const float* hlb, const HgRegs& R) {
;     ...
;     for (int tile = wid; tile < 64; tile += 8) {
;         const int tm = tile >> 3, tn = tile & 7;
;         const f32x4 acc = mma_tile64<true, true>(iT, tm * 16, kdT, tn * 16, lane);
; #pragma unroll
;         for (int j = 0; j < 4; ++j) Sg[(tm * 16 + (lane >> 4) * 4 + j) * 128 + tn * 16 + (lane & 15)] = f2bf(acc[j]);
;     }
	v_mfma_f32_16x16x32_bf16 v[120:123], v[120:123], v[28:31], 0
	v_mfma_f32_16x16x32_bf16 v[120:123], v[124:127], v[32:35], v[120:123]
	s_nop 7
	s_nop 3
	v_mov_b32_e32 v21, v20
	v_bfe_u32 v23, v64, 16, 1
	v_bfe_u32 v26, v65, 16, 1
	v_bfe_u32 v27, v66, 16, 1
	v_bfe_u32 v37, v67, 16, 1
	v_add3_u32 v64, v64, v23, s78
	global_store_short_d16_hi v21, v64, s[22:23]
	v_add3_u32 v65, v65, v26, s78
	global_store_short_d16_hi v21, v65, s[22:23] offset:256
	v_add3_u32 v66, v66, v27, s78
	global_store_short_d16_hi v21, v66, s[22:23] offset:512
	v_add3_u32 v67, v67, v37, s78
	global_store_short_d16_hi v21, v67, s[22:23] offset:768
	v_add_u32_e32 v21, 0x1000, v20
	v_bfe_u32 v23, v72, 16, 1
	v_bfe_u32 v26, v73, 16, 1
	v_bfe_u32 v27, v74, 16, 1
	v_bfe_u32 v37, v75, 16, 1
	v_add3_u32 v72, v72, v23, s78
	global_store_short_d16_hi v21, v72, s[22:23]
	v_add3_u32 v73, v73, v26, s78
	global_store_short_d16_hi v21, v73, s[22:23] offset:256
	v_add3_u32 v74, v74, v27, s78
	global_store_short_d16_hi v21, v74, s[22:23] offset:512
	v_add3_u32 v75, v75, v37, s78
	global_store_short_d16_hi v21, v75, s[22:23] offset:768
	v_add_u32_e32 v21, 0x2000, v20
	v_bfe_u32 v23, v80, 16, 1
	v_bfe_u32 v26, v81, 16, 1
	v_bfe_u32 v27, v82, 16, 1
	v_bfe_u32 v37, v83, 16, 1
	v_add3_u32 v80, v80, v23, s78
	global_store_short_d16_hi v21, v80, s[22:23]
	v_add3_u32 v81, v81, v26, s78
	global_store_short_d16_hi v21, v81, s[22:23] offset:256
	v_add3_u32 v82, v82, v27, s78
	global_store_short_d16_hi v21, v82, s[22:23] offset:512
	v_add3_u32 v83, v83, v37, s78
	global_store_short_d16_hi v21, v83, s[22:23] offset:768
	v_add_u32_e32 v21, 0x3000, v20
	v_bfe_u32 v23, v88, 16, 1
	v_bfe_u32 v26, v89, 16, 1
	v_bfe_u32 v27, v90, 16, 1
	v_bfe_u32 v37, v91, 16, 1
	v_add3_u32 v88, v88, v23, s78
	global_store_short_d16_hi v21, v88, s[22:23]
	v_add3_u32 v89, v89, v26, s78
	global_store_short_d16_hi v21, v89, s[22:23] offset:256
	v_add3_u32 v90, v90, v27, s78
	global_store_short_d16_hi v21, v90, s[22:23] offset:512
	v_add3_u32 v91, v91, v37, s78
	global_store_short_d16_hi v21, v91, s[22:23] offset:768
	v_add_u32_e32 v21, 0x4000, v20
	v_bfe_u32 v23, v96, 16, 1
	v_bfe_u32 v26, v97, 16, 1
	v_bfe_u32 v27, v98, 16, 1
	v_bfe_u32 v37, v99, 16, 1
	v_add3_u32 v96, v96, v23, s78
	global_store_short_d16_hi v21, v96, s[22:23]
	v_add3_u32 v97, v97, v26, s78
	global_store_short_d16_hi v21, v97, s[22:23] offset:256
	v_add3_u32 v98, v98, v27, s78
	global_store_short_d16_hi v21, v98, s[22:23] offset:512
	v_add3_u32 v99, v99, v37, s78
	global_store_short_d16_hi v21, v99, s[22:23] offset:768
	v_add_u32_e32 v21, 0x5000, v20
	v_bfe_u32 v23, v104, 16, 1
	v_bfe_u32 v26, v105, 16, 1
	v_bfe_u32 v27, v106, 16, 1
	v_bfe_u32 v37, v107, 16, 1
	v_add3_u32 v104, v104, v23, s78
	global_store_short_d16_hi v21, v104, s[22:23]
	v_add3_u32 v105, v105, v26, s78
	global_store_short_d16_hi v21, v105, s[22:23] offset:256
	v_add3_u32 v106, v106, v27, s78
	global_store_short_d16_hi v21, v106, s[22:23] offset:512
	v_add3_u32 v107, v107, v37, s78
	global_store_short_d16_hi v21, v107, s[22:23] offset:768
	v_add_u32_e32 v21, 0x6000, v20
	v_bfe_u32 v23, v112, 16, 1
	v_bfe_u32 v26, v113, 16, 1
	v_bfe_u32 v27, v114, 16, 1
	v_bfe_u32 v37, v115, 16, 1
	v_add3_u32 v112, v112, v23, s78
	global_store_short_d16_hi v21, v112, s[22:23]
	v_add3_u32 v113, v113, v26, s78
	global_store_short_d16_hi v21, v113, s[22:23] offset:256
	v_add3_u32 v114, v114, v27, s78
	global_store_short_d16_hi v21, v114, s[22:23] offset:512
	v_add3_u32 v115, v115, v37, s78
	global_store_short_d16_hi v21, v115, s[22:23] offset:768
	v_add_u32_e32 v21, 0x7000, v20
	v_bfe_u32 v23, v120, 16, 1
	v_bfe_u32 v26, v121, 16, 1
	v_bfe_u32 v27, v122, 16, 1
	v_bfe_u32 v37, v123, 16, 1
	v_add3_u32 v120, v120, v23, s78
	global_store_short_d16_hi v21, v120, s[22:23]
	v_add3_u32 v121, v121, v26, s78
	global_store_short_d16_hi v21, v121, s[22:23] offset:256
	v_add3_u32 v122, v122, v27, s78
	global_store_short_d16_hi v21, v122, s[22:23] offset:512
	v_add3_u32 v123, v123, v37, s78
	global_store_short_d16_hi v21, v123, s[22:23] offset:768
	s_branch .LBB0_530

; __device__ __forceinline__ u32x4 pack8(const f32x4& v0, const f32x4& v1) { u32x4 w; w.x = cvt_pk_bf16(v0[0], v0[1]); w.y = cvt_pk_bf16(v0[2], v0[3]); w.z = cvt_pk_bf16(v1[0], v1[1]); w.w = cvt_pk_bf16(v1[2], v1[3]); return w; }
; __device__ __forceinline__ void hg_cum(const u32x4 (&ev)[2], int l, int h, const float* hlb, float* cumS, float* lbS, int tid) {
;     ...
;     __syncthreads();
; #pragma unroll
;     for (int tt = 0; tt < 16; ++tt) cumS[(seg * 16 + tt) * 128 + k] += off;
; __device__ __forceinline__ void hgC_item(const Bufs& B, int l, int it, unsigned char* shm, const float* hlb, const float* hn) {
;     ...
;     for (int q = 0; q < 2; ++q) {
;         const int idx = tid + 512 * q, t = idx >> 4, k8 = (idx & 15) * 8;
;         f32x4 q0, q1, e0, e1; unpack8(qv[q], q0, q1); unpack8(ev[q], e0, e1);
;         const u32x4 iw = iv[q];
;         const int tx = t ^ (((k8 >> 3) & 7) << 3);
;         const f32x4 c0 = *(const f32x4*)(cumS + t * 128 + k8), c1 = *(const f32x4*)(cumS + t * 128 + k8 + 4), m0v = *(const f32x4*)(cumS + 31 * 128 + k8), m1v = *(const f32x4*)(cumS + 31 * 128 + k8 + 4);
;         const f32x4 l0 = *(const f32x4*)(lbS + k8), l1 = *(const f32x4*)(lbS + k8 + 4);
;         f32x4 x0, x1, y0, y1, z0, z1;
; #pragma unroll
;         for (int j = 0; j < 4; ++j) {
;             x0[j] = q0[j] * __expf(c0[j]); x1[j] = q1[j] * __expf(c1[j]);
;             y0[j] = q0[j] * __expf(fminf(c0[j] - m0v[j], 80.f)); y1[j] = q1[j] * __expf(fminf(c1[j] - m1v[j], 80.f));
;             z0[j] = l0[j] * e0[j] * __expf(fminf(m0v[j] - c0[j], 80.f)); z1[j] = l1[j] * e1[j] * __expf(fminf(m1v[j] - c1[j], 80.f));
;         }
;         *(u32x4*)(qe + t * 136 + k8) = pack8(x0, x1); *(u32x4*)(qa + t * 136 + k8) = pack8(y0, y1); *(u32x4*)(kb + t * 136 + k8) = pack8(z0, z1);
;         iT[(k8 + 0) * 72 + tx] = (bf16_t)(iw.x & 0xffffu); iT[(k8 + 1) * 72 + tx] = (bf16_t)(iw.x >> 16); iT[(k8 + 2) * 72 + tx] = (bf16_t)(iw.y & 0xffffu); iT[(k8 + 3) * 72 + tx] = (bf16_t)(iw.y >> 16);
;         iT[(k8 + 4) * 72 + tx] = (bf16_t)(iw.z & 0xffffu); iT[(k8 + 5) * 72 + tx] = (bf16_t)(iw.z >> 16); iT[(k8 + 6) * 72 + tx] = (bf16_t)(iw.w & 0xffffu); iT[(k8 + 7) * 72 + tx] = (bf16_t)(iw.w >> 16);
.LBB0_828:
	s_or_b64 exec, exec, s[2:3]
	s_barrier
	ds_read2st64_b32 v[34:35], v32 offset1:2
	v_lshlrev_b32_e32 v38, 16, v28
	v_and_b32_e32 v39, 0xffff0000, v28
	v_lshlrev_b32_e32 v86, 16, v29
	v_and_b32_e32 v87, 0xffff0000, v29
	s_waitcnt lgkmcnt(0)
	v_add_f32_e32 v34, v33, v34
	v_add_f32_e32 v35, v33, v35
	ds_write2st64_b32 v32, v34, v35 offset1:2
	ds_read2st64_b32 v[34:35], v32 offset0:4 offset1:6
	v_lshlrev_b32_e32 v88, 16, v30
	v_and_b32_e32 v89, 0xffff0000, v30
	v_lshlrev_b32_e32 v90, 16, v31
	v_and_b32_e32 v91, 0xffff0000, v31
	s_waitcnt lgkmcnt(0)
	v_add_f32_e32 v34, v33, v34
	v_add_f32_e32 v35, v33, v35
	ds_write2st64_b32 v32, v34, v35 offset0:4 offset1:6
	ds_read2st64_b32 v[34:35], v32 offset0:8 offset1:10
	v_sub_u32_e32 v100, v48, v42
	v_cmp_gt_i32_e32 vcc, 16, v66
	s_waitcnt lgkmcnt(0)
	v_add_f32_e32 v34, v33, v34
	v_add_f32_e32 v35, v33, v35
	ds_write2st64_b32 v32, v34, v35 offset0:8 offset1:10
	ds_read2st64_b32 v[34:35], v32 offset0:12 offset1:14
	s_waitcnt lgkmcnt(0)
	v_add_f32_e32 v34, v33, v34
	v_add_f32_e32 v35, v33, v35
	ds_write2st64_b32 v32, v34, v35 offset0:12 offset1:14
	ds_read2st64_b32 v[34:35], v32 offset0:16 offset1:18
	s_waitcnt lgkmcnt(0)
	v_add_f32_e32 v34, v33, v34
	v_add_f32_e32 v35, v33, v35
	ds_write2st64_b32 v32, v34, v35 offset0:16 offset1:18
	ds_read2st64_b32 v[34:35], v32 offset0:20 offset1:22
	s_waitcnt lgkmcnt(0)
	v_add_f32_e32 v34, v33, v34
	v_add_f32_e32 v35, v33, v35
	ds_write2st64_b32 v32, v34, v35 offset0:20 offset1:22
	ds_read2st64_b32 v[34:35], v32 offset0:24 offset1:26
	s_waitcnt lgkmcnt(0)
	v_add_f32_e32 v34, v33, v34
	v_add_f32_e32 v35, v33, v35
	ds_write2st64_b32 v32, v34, v35 offset0:24 offset1:26
	ds_read2st64_b32 v[34:35], v32 offset0:28 offset1:30
	s_waitcnt lgkmcnt(0)
	v_add_f32_e32 v34, v33, v34
	v_add_f32_e32 v33, v33, v35
	ds_write2st64_b32 v32, v34, v33 offset0:28 offset1:30
	v_lshl_add_u32 v34, v43, 9, v48
	s_waitcnt lgkmcnt(0)
	s_barrier
	ds_read_b128 v[28:31], v34
	ds_read_b128 v[34:37], v34 offset:16
	ds_read_b128 v[70:73], v48 offset:15872
	ds_read_b128 v[74:77], v48 offset:15888
	ds_read_b128 v[78:81], v69
	ds_read_b128 v[82:85], v69 offset:16
	s_waitcnt lgkmcnt(4)
	v_mul_f32_e32 v93, 0x3fb8aa3b, v34
	v_exp_f32_e32 v94, v93
	s_waitcnt lgkmcnt(3)
	v_sub_f32_e32 v93, v28, v70
	v_min_f32_e32 v93, 0x42a00000, v93
	v_mul_f32_e32 v93, 0x3fb8aa3b, v93
	v_exp_f32_e32 v96, v93
	s_waitcnt lgkmcnt(2)
	v_sub_f32_e32 v93, v34, v74
	v_min_f32_e32 v93, 0x42a00000, v93
	v_mul_f32_e32 v92, 0x3fb8aa3b, v28
	v_mul_f32_e32 v93, 0x3fb8aa3b, v93
	v_sub_f32_e32 v28, v70, v28
	v_mul_f32_e32 v70, 0x3fb8aa3b, v29
	v_exp_f32_e32 v98, v93
	v_exp_f32_e32 v93, v70
	v_mul_f32_e32 v70, 0x3fb8aa3b, v35
	v_exp_f32_e32 v95, v70
	v_sub_f32_e32 v70, v29, v71
	v_sub_f32_e32 v29, v71, v29
	v_min_f32_e32 v28, 0x42a00000, v28
	v_min_f32_e32 v29, 0x42a00000, v29
	v_mul_f32_e32 v28, 0x3fb8aa3b, v28
	v_mul_f32_e32 v29, 0x3fb8aa3b, v29
	v_exp_f32_e32 v28, v28
	v_exp_f32_e32 v29, v29
	s_waitcnt lgkmcnt(1)
	v_pk_mul_f32 v[56:57], v[78:79], v[56:57]
	v_sub_f32_e32 v34, v74, v34
	v_min_f32_e32 v34, 0x42a00000, v34
	v_pk_mul_f32 v[56:57], v[56:57], v[28:29]
	v_sub_f32_e32 v28, v75, v35
	v_min_f32_e32 v70, 0x42a00000, v70
	v_min_f32_e32 v28, 0x42a00000, v28
	v_mul_f32_e32 v34, 0x3fb8aa3b, v34
	v_mul_f32_e32 v70, 0x3fb8aa3b, v70
	v_mul_f32_e32 v28, 0x3fb8aa3b, v28
	v_exp_f32_e32 v34, v34
	v_exp_f32_e32 v97, v70
	v_sub_f32_e32 v70, v35, v75
	v_exp_f32_e32 v35, v28
	s_waitcnt lgkmcnt(0)
	v_pk_mul_f32 v[28:29], v[82:83], v[54:55]
	v_min_f32_e32 v70, 0x42a00000, v70
	v_mul_f32_e32 v70, 0x3fb8aa3b, v70
	v_pk_mul_f32 v[34:35], v[28:29], v[34:35]
	v_mul_f32_e32 v29, 0x3fb8aa3b, v36
	v_exp_f32_e32 v54, v29
	v_sub_f32_e32 v29, v30, v72
	v_min_f32_e32 v29, 0x42a00000, v29
	v_mul_f32_e32 v29, 0x3fb8aa3b, v29
	v_exp_f32_e32 v99, v70
	v_exp_f32_e32 v70, v29
	v_sub_f32_e32 v29, v36, v76
	v_min_f32_e32 v29, 0x42a00000, v29
	v_mul_f32_e32 v29, 0x3fb8aa3b, v29
	v_exp_f32_e32 v74, v29
	v_sub_f32_e32 v29, v72, v30
	v_min_f32_e32 v29, 0x42a00000, v29
	v_mul_f32_e32 v29, 0x3fb8aa3b, v29
	v_mul_f32_e32 v28, 0x3fb8aa3b, v30
	v_exp_f32_e32 v30, v29
	v_sub_f32_e32 v29, v76, v36
	v_min_f32_e32 v29, 0x42a00000, v29
	v_mul_f32_e32 v29, 0x3fb8aa3b, v29
	v_exp_f32_e32 v36, v29
	v_mul_f32_e32 v29, 0x3fb8aa3b, v31
	v_exp_f32_e32 v28, v28
	v_exp_f32_e32 v29, v29
	v_sub_f32_e32 v71, v31, v73
	v_exp_f32_e32 v92, v92
	v_mul_f32_e32 v55, 0x3fb8aa3b, v37
	v_pk_mul_f32 v[78:79], v[28:29], v[86:87]
	v_sub_f32_e32 v28, v37, v77
	v_min_f32_e32 v28, 0x42a00000, v28
	v_mul_f32_e32 v28, 0x3fb8aa3b, v28
	v_exp_f32_e32 v75, v28
	v_sub_f32_e32 v28, v73, v31
	v_min_f32_e32 v28, 0x42a00000, v28
	v_mul_f32_e32 v28, 0x3fb8aa3b, v28
	v_exp_f32_e32 v31, v28
	v_pk_mul_f32 v[28:29], v[80:81], v[52:53]
	v_min_f32_e32 v71, 0x42a00000, v71
	v_exp_f32_e32 v55, v55
	v_pk_mul_f32 v[52:53], v[28:29], v[30:31]
	v_sub_f32_e32 v28, v77, v37
	v_min_f32_e32 v28, 0x42a00000, v28
	v_mul_f32_e32 v28, 0x3fb8aa3b, v28
	v_mul_f32_e32 v71, 0x3fb8aa3b, v71
	v_exp_f32_e32 v37, v28
	v_exp_f32_e32 v71, v71
	v_pk_mul_f32 v[96:97], v[96:97], v[38:39]
	v_pk_mul_f32 v[38:39], v[92:93], v[38:39]
	v_pk_mul_f32 v[28:29], v[84:85], v[50:51]
	v_pk_mul_f32 v[92:93], v[98:99], v[88:89]
	v_pk_mul_f32 v[88:89], v[94:95], v[88:89]
	v_pk_mul_f32 v[54:55], v[54:55], v[90:91]
	v_pk_mul_f32 v[36:37], v[28:29], v[36:37]
	v_cvt_pk_bf16_f32 v28, v38, v39
	v_mul_lo_u32 v38, v43, s77
	v_pk_mul_f32 v[70:71], v[70:71], v[86:87]
	v_pk_mul_f32 v[74:75], v[74:75], v[90:91]
	v_cvt_pk_bf16_f32 v29, v78, v79
	v_cvt_pk_bf16_f32 v30, v88, v89
	v_cvt_pk_bf16_f32 v31, v54, v55
	v_add_u32_e32 v39, v100, v38
	v_add_u32_e32 v32, s46, v42
	v_mov_b32_e32 v33, s84
	ds_write_b128 v39, v[28:31] offset:33792
	v_cvt_pk_bf16_f32 v28, v96, v97
	v_cvt_pk_bf16_f32 v29, v70, v71
	v_cvt_pk_bf16_f32 v30, v92, v93
	v_cvt_pk_bf16_f32 v31, v74, v75
	v_mad_u32_u24 v33, v65, s76, v33
	v_bitop3_b32 v50, v68, v43, 56 bitop3:0x6c
	ds_write_b128 v39, v[28:31] offset:51200
	v_cvt_pk_bf16_f32 v28, v56, v57
	v_cvt_pk_bf16_f32 v29, v52, v53
	v_cvt_pk_bf16_f32 v30, v34, v35
	v_cvt_pk_bf16_f32 v31, v36, v37
	v_add_u32_e32 v34, v32, v38
	ds_write_b128 v34, v[28:31]
	v_lshl_add_u32 v28, v50, 1, v33
	ds_write_b16 v28, v24
	ds_write_b16_d16_hi v28, v24 offset:144
	ds_write_b16 v28, v25 offset:288
	ds_write_b16_d16_hi v28, v25 offset:432
	ds_write_b16 v28, v26 offset:576
	ds_write_b16_d16_hi v28, v26 offset:720
	ds_write_b16 v28, v27 offset:864
	ds_write_b16_d16_hi v28, v27 offset:1008
	v_lshl_add_u32 v24, v49, 9, v48
	v_lshlrev_b32_e32 v38, 16, v20
	v_and_b32_e32 v39, 0xffff0000, v20
	v_lshlrev_b32_e32 v70, 16, v21
	v_and_b32_e32 v71, 0xffff0000, v21
	v_lshlrev_b32_e32 v72, 16, v22
	v_and_b32_e32 v73, 0xffff0000, v22
	v_lshlrev_b32_e32 v74, 16, v23
	v_and_b32_e32 v75, 0xffff0000, v23
	ds_read_b128 v[20:23], v24
	ds_read_b128 v[24:27], v24 offset:16
	ds_read_b128 v[28:31], v48 offset:15872
	ds_read_b128 v[34:37], v48 offset:15888
	ds_read_b128 v[50:53], v69
	ds_read_b128 v[54:57], v69 offset:16
	s_waitcnt lgkmcnt(5)
; __device__ __forceinline__ u32x4 pack8(const f32x4& v0, const f32x4& v1) { u32x4 w; w.x = cvt_pk_bf16(v0[0], v0[1]); w.y = cvt_pk_bf16(v0[2], v0[3]); w.z = cvt_pk_bf16(v1[0], v1[1]); w.w = cvt_pk_bf16(v1[2], v1[3]); return w; }
; __device__ __forceinline__ void unpack8(const u32x4& w, f32x4& v0, f32x4& v1) { v0[0] = bflo(w.x); v0[1] = bfhi(w.x); v0[2] = bflo(w.y); v0[3] = bfhi(w.y); v1[0] = bflo(w.z); v1[1] = bfhi(w.z); v1[2] = bflo(w.w); v1[3] = bfhi(w.w); }
; __device__ __forceinline__ void hgC_item(const Bufs& B, int l, int it, unsigned char* shm, const float* hlb, const float* hn) {
;     ...
;     for (int q = 0; q < 2; ++q) {
;         const int idx = tid + 512 * q, t = idx >> 4, k8 = (idx & 15) * 8;
;         f32x4 q0, q1, e0, e1; unpack8(qv[q], q0, q1); unpack8(ev[q], e0, e1);
;         const u32x4 iw = iv[q];
;         const int tx = t ^ (((k8 >> 3) & 7) << 3);
;         const f32x4 c0 = *(const f32x4*)(cumS + t * 128 + k8), c1 = *(const f32x4*)(cumS + t * 128 + k8 + 4), m0v = *(const f32x4*)(cumS + 31 * 128 + k8), m1v = *(const f32x4*)(cumS + 31 * 128 + k8 + 4);
;         const f32x4 l0 = *(const f32x4*)(lbS + k8), l1 = *(const f32x4*)(lbS + k8 + 4);
;         f32x4 x0, x1, y0, y1, z0, z1;
; #pragma unroll
;         for (int j = 0; j < 4; ++j) {
;             x0[j] = q0[j] * __expf(c0[j]); x1[j] = q1[j] * __expf(c1[j]);
;             y0[j] = q0[j] * __expf(fminf(c0[j] - m0v[j], 80.f)); y1[j] = q1[j] * __expf(fminf(c1[j] - m1v[j], 80.f));
;             z0[j] = l0[j] * e0[j] * __expf(fminf(m0v[j] - c0[j], 80.f)); z1[j] = l1[j] * e1[j] * __expf(fminf(m1v[j] - c1[j], 80.f));
;         }
;         *(u32x4*)(qe + t * 136 + k8) = pack8(x0, x1); *(u32x4*)(qa + t * 136 + k8) = pack8(y0, y1); *(u32x4*)(kb + t * 136 + k8) = pack8(z0, z1);
;         iT[(k8 + 0) * 72 + tx] = (bf16_t)(iw.x & 0xffffu); iT[(k8 + 1) * 72 + tx] = (bf16_t)(iw.x >> 16); iT[(k8 + 2) * 72 + tx] = (bf16_t)(iw.y & 0xffffu); iT[(k8 + 3) * 72 + tx] = (bf16_t)(iw.y >> 16);
;         iT[(k8 + 4) * 72 + tx] = (bf16_t)(iw.z & 0xffffu); iT[(k8 + 5) * 72 + tx] = (bf16_t)(iw.z >> 16); iT[(k8 + 6) * 72 + tx] = (bf16_t)(iw.w & 0xffffu); iT[(k8 + 7) * 72 + tx] = (bf16_t)(iw.w >> 16);
;     }
;     __syncthreads();
	v_mul_f32_e32 v69, 0x3fb8aa3b, v20
	v_exp_f32_e32 v76, v69
	s_waitcnt lgkmcnt(4)
	v_mul_f32_e32 v69, 0x3fb8aa3b, v24
	v_exp_f32_e32 v78, v69
	s_waitcnt lgkmcnt(3)
	v_sub_f32_e32 v69, v20, v28
	v_sub_f32_e32 v20, v28, v20
	v_mul_f32_e32 v28, 0x3fb8aa3b, v21
	v_exp_f32_e32 v77, v28
	v_mul_f32_e32 v28, 0x3fb8aa3b, v25
	v_exp_f32_e32 v79, v28
	v_sub_f32_e32 v28, v21, v29
	v_sub_f32_e32 v21, v29, v21
	v_min_f32_e32 v20, 0x42a00000, v20
	v_min_f32_e32 v28, 0x42a00000, v28
	v_min_f32_e32 v21, 0x42a00000, v21
	v_mul_f32_e32 v20, 0x3fb8aa3b, v20
	v_mul_f32_e32 v28, 0x3fb8aa3b, v28
	v_mul_f32_e32 v21, 0x3fb8aa3b, v21
	v_exp_f32_e32 v20, v20
	v_exp_f32_e32 v81, v28
	s_waitcnt lgkmcnt(2)
	v_sub_f32_e32 v28, v25, v35
	v_exp_f32_e32 v21, v21
	v_min_f32_e32 v28, 0x42a00000, v28
	v_min_f32_e32 v69, 0x42a00000, v69
	v_mul_f32_e32 v28, 0x3fb8aa3b, v28
	v_mul_f32_e32 v69, 0x3fb8aa3b, v69
	v_exp_f32_e32 v83, v28
	s_waitcnt lgkmcnt(1)
	v_pk_mul_f32 v[28:29], v[50:51], v[62:63]
	v_exp_f32_e32 v80, v69
	v_sub_f32_e32 v69, v24, v34
	v_sub_f32_e32 v24, v34, v24
	v_pk_mul_f32 v[28:29], v[28:29], v[20:21]
	v_sub_f32_e32 v20, v35, v25
	v_min_f32_e32 v24, 0x42a00000, v24
	v_min_f32_e32 v20, 0x42a00000, v20
	v_mul_f32_e32 v24, 0x3fb8aa3b, v24
	v_mul_f32_e32 v20, 0x3fb8aa3b, v20
	v_exp_f32_e32 v24, v24
	v_exp_f32_e32 v25, v20
	s_waitcnt lgkmcnt(0)
	v_pk_mul_f32 v[20:21], v[54:55], v[60:61]
	v_min_f32_e32 v69, 0x42a00000, v69
	v_mul_f32_e32 v69, 0x3fb8aa3b, v69
	v_pk_mul_f32 v[24:25], v[20:21], v[24:25]
	v_mul_f32_e32 v21, 0x3fb8aa3b, v26
	v_exp_f32_e32 v34, v21
	v_sub_f32_e32 v21, v22, v30
	v_min_f32_e32 v21, 0x42a00000, v21
	v_mul_f32_e32 v21, 0x3fb8aa3b, v21
	v_exp_f32_e32 v50, v21
	v_sub_f32_e32 v21, v26, v36
	v_min_f32_e32 v21, 0x42a00000, v21
	v_mul_f32_e32 v21, 0x3fb8aa3b, v21
	v_exp_f32_e32 v54, v21
	v_sub_f32_e32 v21, v30, v22
	v_min_f32_e32 v21, 0x42a00000, v21
	v_mul_f32_e32 v21, 0x3fb8aa3b, v21
	v_mul_f32_e32 v20, 0x3fb8aa3b, v22
	v_exp_f32_e32 v22, v21
	v_sub_f32_e32 v21, v36, v26
	v_min_f32_e32 v21, 0x42a00000, v21
	v_mul_f32_e32 v21, 0x3fb8aa3b, v21
	v_exp_f32_e32 v26, v21
	v_mul_f32_e32 v21, 0x3fb8aa3b, v23
	v_exp_f32_e32 v20, v20
	v_exp_f32_e32 v21, v21
	v_mul_f32_e32 v30, 0x3fb8aa3b, v27
	v_exp_f32_e32 v35, v30
	v_sub_f32_e32 v30, v23, v31
	v_pk_mul_f32 v[60:61], v[20:21], v[70:71]
	v_sub_f32_e32 v20, v27, v37
	v_min_f32_e32 v20, 0x42a00000, v20
	v_mul_f32_e32 v20, 0x3fb8aa3b, v20
	v_exp_f32_e32 v55, v20
	v_sub_f32_e32 v20, v31, v23
	v_min_f32_e32 v20, 0x42a00000, v20
	v_mul_f32_e32 v20, 0x3fb8aa3b, v20
	v_exp_f32_e32 v23, v20
	v_min_f32_e32 v30, 0x42a00000, v30
	v_mul_f32_e32 v30, 0x3fb8aa3b, v30
	v_pk_mul_f32 v[20:21], v[52:53], v[58:59]
	v_exp_f32_e32 v51, v30
	v_pk_mul_f32 v[30:31], v[20:21], v[22:23]
	v_sub_f32_e32 v20, v37, v27
	v_min_f32_e32 v20, 0x42a00000, v20
	v_exp_f32_e32 v82, v69
	v_mul_f32_e32 v20, 0x3fb8aa3b, v20
	v_exp_f32_e32 v27, v20
	v_pk_mul_f32 v[34:35], v[34:35], v[74:75]
	v_pk_mul_f32 v[80:81], v[80:81], v[38:39]
	v_pk_mul_f32 v[38:39], v[76:77], v[38:39]
	v_pk_mul_f32 v[76:77], v[82:83], v[72:73]
	v_pk_mul_f32 v[72:73], v[78:79], v[72:73]
	v_pk_mul_f32 v[20:21], v[56:57], v[40:41]
	v_cvt_pk_bf16_f32 v23, v34, v35
	v_mul_lo_u32 v34, v49, s77
	v_pk_mul_f32 v[50:51], v[50:51], v[70:71]
	v_pk_mul_f32 v[54:55], v[54:55], v[74:75]
	v_pk_mul_f32 v[26:27], v[20:21], v[26:27]
	v_cvt_pk_bf16_f32 v20, v38, v39
	v_cvt_pk_bf16_f32 v21, v60, v61
	v_cvt_pk_bf16_f32 v22, v72, v73
	v_add_u32_e32 v35, v100, v34
	ds_write_b128 v35, v[20:23] offset:33792
	v_cvt_pk_bf16_f32 v20, v80, v81
	v_cvt_pk_bf16_f32 v21, v50, v51
	v_cvt_pk_bf16_f32 v22, v76, v77
	v_cvt_pk_bf16_f32 v23, v54, v55
	v_bitop3_b32 v36, v49, v68, 56 bitop3:0x78
	ds_write_b128 v35, v[20:23] offset:51200
	v_cvt_pk_bf16_f32 v20, v28, v29
	v_cvt_pk_bf16_f32 v21, v30, v31
	v_cvt_pk_bf16_f32 v22, v24, v25
	v_cvt_pk_bf16_f32 v23, v26, v27
	v_add_u32_e32 v24, v32, v34
	ds_write_b128 v24, v[20:23]
	v_lshl_add_u32 v20, v36, 1, v33
	s_waitcnt vmcnt(0)
	ds_write_b16 v20, v16
	ds_write_b16_d16_hi v20, v16 offset:144
	ds_write_b16 v20, v17 offset:288
	ds_write_b16_d16_hi v20, v17 offset:432
	ds_write_b16 v20, v18 offset:576
	ds_write_b16_d16_hi v20, v18 offset:720
	ds_write_b16 v20, v19 offset:864
	ds_write_b16_d16_hi v20, v19 offset:1008
	v_lshrrev_b32_e32 v16, 2, v67
	v_and_b32_e32 v21, 15, v67
	v_and_b32_e32 v23, 12, v16
	s_waitcnt lgkmcnt(0)
	s_barrier
; __device__ __forceinline__ bf16_t f2bf(float f) { unsigned u = __float_as_uint(f); u += 0x7FFFu + ((u >> 16) & 1u); return (bf16_t)(u >> 16); }
; __device__ __forceinline__ f32x4 mma_tile(const bf16_t* A, int lda, const bf16_t* Bt, int ldb, int K, int lane) {
;     ...
;     for (int k = 0; k < K; k += 32) {
;         const bf16x8 a = *(const bf16x8*)(ap + k), b = *(const bf16x8*)(bp + k);
;         acc = __builtin_amdgcn_mfma_f32_16x16x32_bf16(a, b, acc, 0, 0, 0);
;     }
; __device__ __forceinline__ void hgC_item(const Bufs& B, int l, int it, unsigned char* shm, const float* hlb, const float* hn) {
;     ...
;     for (int tile = wid; tile < 16; tile += 8) {
;         const int tm = tile >> 2, tn = tile & 3;
;         f32x4 acc = {0.f, 0.f, 0.f, 0.f};
;         if (tn <= tm) acc = mma_tile(qa + tm * 16 * 136, 136, kb + tn * 16 * 136, 136, 128, lane);
;         const int sc = tn * 16 + (lane & 15);
; #pragma unroll
;         for (int j = 0; j < 4; ++j) { const int t = tm * 16 + (lane >> 4) * 4 + j; P[t * 72 + sc] = f2bf(sc <= t ? acc[j] : 0.f); }
;     }
	s_mov_b64 s[2:3], exec
	v_readfirstlane_b32 s34, v66
	v_mad_u32_u24 v20, v21, s77, v176
	v_and_b32_e32 v24, 3, v66
	v_mul_u32_u24_e32 v17, 0x1100, v24
	v_lshl_or_b32 v25, v24, 4, v21
	v_add3_u32 v26, s46, v20, v17
	v_lshl_add_u32 v22, v25, 1, s47
	s_lshr_b32 s34, s34, 2
	s_mul_i32 s35, s34, 0x1100
	s_lshl_b32 s34, s34, 4
	ds_read_b128 v[80:83], v26
	ds_read_b128 v[84:87], v26 offset:64
	ds_read_b128 v[88:91], v26 offset:128
	ds_read_b128 v[92:95], v26 offset:192
	v_add_u32_e32 v27, s35, v20
	ds_read_b128 v[96:99], v27 offset:51200
	ds_read_b128 v[100:103], v27 offset:51264
	ds_read_b128 v[104:107], v27 offset:51328
	ds_read_b128 v[108:111], v27 offset:51392
	ds_read_b128 v[112:115], v27 offset:59904
	ds_read_b128 v[116:119], v27 offset:59968
	ds_read_b128 v[120:123], v27 offset:60032
	ds_read_b128 v[124:127], v27 offset:60096
	v_add_u32_e32 v72, s34, v23
	v_mad_u32_u24 v75, v72, s76, v22
	s_waitcnt lgkmcnt(3)
	v_mfma_f32_16x16x32_bf16 v[60:63], v[96:99], v[80:83], 0
	v_mfma_f32_16x16x32_bf16 v[68:71], v[112:115], v[80:83], 0
	s_waitcnt lgkmcnt(2)
	v_mfma_f32_16x16x32_bf16 v[60:63], v[100:103], v[84:87], v[60:63]
	v_mfma_f32_16x16x32_bf16 v[68:71], v[116:119], v[84:87], v[68:71]
	s_waitcnt lgkmcnt(1)
	v_mfma_f32_16x16x32_bf16 v[60:63], v[104:107], v[88:91], v[60:63]
	v_mfma_f32_16x16x32_bf16 v[68:71], v[120:123], v[88:91], v[68:71]
	s_waitcnt lgkmcnt(0)
	v_mfma_f32_16x16x32_bf16 v[60:63], v[108:111], v[92:95], v[60:63]
	v_mfma_f32_16x16x32_bf16 v[68:71], v[124:127], v[92:95], v[68:71]
	s_nop 7
	s_nop 3
	v_add_u32_e32 v73, 1, v72
	v_add_u32_e32 v74, 2, v72
	v_add_u32_e32 v76, 3, v72
	v_cmp_le_i32_e64 s[36:37], v25, v72
	v_cmp_le_i32_e64 s[38:39], v25, v73
	v_cmp_le_i32_e64 s[40:41], v25, v74
	v_cmp_le_i32_e64 vcc, v25, v76
	v_cndmask_b32_e64 v60, 0, v60, s[36:37]
	v_cndmask_b32_e64 v61, 0, v61, s[38:39]
	v_cndmask_b32_e64 v62, 0, v62, s[40:41]
	v_cndmask_b32_e64 v63, 0, v63, vcc
	v_bfe_u32 v77, v60, 16, 1
	v_bfe_u32 v73, v61, 16, 1
	v_bfe_u32 v74, v62, 16, 1
	v_bfe_u32 v76, v63, 16, 1
	v_add3_u32 v60, v60, v77, s78
	ds_write_b16_d16_hi v75, v60
	v_add3_u32 v61, v61, v73, s78
	ds_write_b16_d16_hi v75, v61 offset:144
	v_add3_u32 v62, v62, v74, s78
	ds_write_b16_d16_hi v75, v62 offset:288
	v_add3_u32 v63, v63, v76, s78
	ds_write_b16_d16_hi v75, v63 offset:432
	v_add_u32_e32 v72, 32, v72
	v_add_u32_e32 v73, 1, v72
	v_add_u32_e32 v74, 2, v72
	v_add_u32_e32 v76, 3, v72
	v_cmp_le_i32_e64 s[36:37], v25, v72
	v_cmp_le_i32_e64 s[38:39], v25, v73
	v_cmp_le_i32_e64 s[40:41], v25, v74
	v_cmp_le_i32_e64 vcc, v25, v76
	v_cndmask_b32_e64 v68, 0, v68, s[36:37]
	v_cndmask_b32_e64 v69, 0, v69, s[38:39]
	v_cndmask_b32_e64 v70, 0, v70, s[40:41]
	v_cndmask_b32_e64 v71, 0, v71, vcc
	v_bfe_u32 v77, v68, 16, 1
	v_bfe_u32 v73, v69, 16, 1
	v_bfe_u32 v74, v70, 16, 1
	v_bfe_u32 v76, v71, 16, 1
	v_add3_u32 v68, v68, v77, s78
	ds_write_b16_d16_hi v75, v68 offset:4608
	v_add3_u32 v69, v69, v73, s78
	ds_write_b16_d16_hi v75, v69 offset:4752
	v_add3_u32 v70, v70, v74, s78
	ds_write_b16_d16_hi v75, v70 offset:4896
	v_add3_u32 v71, v71, v76, s78
	ds_write_b16_d16_hi v75, v71 offset:5040
